# ssd_norm: four items per pass with all loads issued together and the four reduction chains interleaved (leftover items use the original loop)
# speedup vs baseline: 1.0057x; 1.0057x over previous
; DI float siluf_(float x) { return x * sigmoidf_(x); }
; DI void unpack8(const u32x4& w, float* f) { f[0] = bflo(w.x); f[1] = bfhi(w.x); f[2] = bflo(w.y); f[3] = bfhi(w.y); f[4] = bflo(w.z); f[5] = bfhi(w.z); f[6] = bflo(w.w); f[7] = bfhi(w.w); }
; DI u32x4 pack8(const float* f) { u32x4 w; w.x = pk2(f[0], f[1]); w.y = pk2(f[2], f[3]); w.z = pk2(f[4], f[5]); w.w = pk2(f[6], f[7]); return w; }
; DI float rs_of(float ss, float inv_n) { return __builtin_amdgcn_rsqf(ss * inv_n + EPS); }
; DI void ssd_norm(const Params& P) {
;     ...
;     for (int item = gw; item < T * 4; item += NW) { const size_t off = (size_t)(item >> 2) * 2048 + (item & 3) * 512 + lane * 8;
;         const u32x4 yw = *(const u32x4*)(YB + off), zw = *(const u32x4*)(Z + off); float f[8], z[8]; unpack8(yw, f); unpack8(zw, z);
;         float sq = 0.f;
; #pragma unroll
;         for (int j = 0; j < 8; ++j) { f[j] *= siluf_(z[j]); sq += f[j] * f[j]; }
; #pragma unroll
;         for (int o = 32; o >= 1; o >>= 1) sq += __shfl_xor(sq, o);
;         const float rs = rs_of(sq, 1.f / 512.f);
; #pragma unroll
;         for (int j = 0; j < 8; ++j) f[j] *= rs;
;         *(u32x4*)(YB + off) = pack8(f); }
.Lnorm4:
	v_readfirstlane_b32 s14, v1
	s_mul_i32 s15, s3, 3
	s_nop 1
	s_add_i32 s14, s14, s15
	s_cmp_gt_i32 s14, 0x107ff
	s_cbranch_scc1 .LBB0_166
	v_ashrrev_i32_e32 v42, 2, v1
	v_ashrrev_i32_e32 v43, 31, v42
	v_lshlrev_b64 v[42:43], 11, v[42:43]
	s_movk_i32 s13, 0x600
	v_and_or_b32 v41, v8, s13, v42
	v_or_b32_e32 v42, v41, v0
	v_lshlrev_b64 v[46:47], 1, v[42:43]
	v_lshl_add_u64 v[50:51], s[8:9], 0, v[46:47]
	v_lshl_add_u64 v[46:47], s[6:7], 0, v[46:47]
	global_load_dwordx4 v[42:45], v[50:51], off
	v_add_u32_e32 v1, s3, v1
	global_load_dwordx4 v[46:49], v[46:47], off
	v_add_u32_e32 v8, s12, v8
	v_ashrrev_i32_e32 v74, 2, v1
	v_ashrrev_i32_e32 v75, 31, v74
	v_lshlrev_b64 v[74:75], 11, v[74:75]
	s_movk_i32 s13, 0x600
	v_and_or_b32 v73, v8, s13, v74
	v_or_b32_e32 v74, v73, v0
	v_lshlrev_b64 v[78:79], 1, v[74:75]
	v_lshl_add_u64 v[82:83], s[8:9], 0, v[78:79]
	v_lshl_add_u64 v[78:79], s[6:7], 0, v[78:79]
	global_load_dwordx4 v[74:77], v[82:83], off
	v_add_u32_e32 v1, s3, v1
	global_load_dwordx4 v[78:81], v[78:79], off
	v_add_u32_e32 v8, s12, v8
	v_ashrrev_i32_e32 v106, 2, v1
	v_ashrrev_i32_e32 v107, 31, v106
	v_lshlrev_b64 v[106:107], 11, v[106:107]
	s_movk_i32 s13, 0x600
	v_and_or_b32 v105, v8, s13, v106
	v_or_b32_e32 v106, v105, v0
	v_lshlrev_b64 v[110:111], 1, v[106:107]
	v_lshl_add_u64 v[114:115], s[8:9], 0, v[110:111]
	v_lshl_add_u64 v[110:111], s[6:7], 0, v[110:111]
	global_load_dwordx4 v[106:109], v[114:115], off
	v_add_u32_e32 v1, s3, v1
	global_load_dwordx4 v[110:113], v[110:111], off
	v_add_u32_e32 v8, s12, v8
	v_ashrrev_i32_e32 v138, 2, v1
	v_ashrrev_i32_e32 v139, 31, v138
	v_lshlrev_b64 v[138:139], 11, v[138:139]
	s_movk_i32 s13, 0x600
	v_and_or_b32 v137, v8, s13, v138
	v_or_b32_e32 v138, v137, v0
	v_lshlrev_b64 v[142:143], 1, v[138:139]
	v_lshl_add_u64 v[146:147], s[8:9], 0, v[142:143]
	v_lshl_add_u64 v[142:143], s[6:7], 0, v[142:143]
	global_load_dwordx4 v[138:141], v[146:147], off
	v_add_u32_e32 v1, s3, v1
	global_load_dwordx4 v[142:145], v[142:143], off
	v_add_u32_e32 v8, s12, v8
	s_waitcnt vmcnt(0)
	v_lshlrev_b32_e32 v52, 16, v45
	v_lshlrev_b32_e32 v84, 16, v77
	v_lshlrev_b32_e32 v116, 16, v109
	v_lshlrev_b32_e32 v148, 16, v141
	v_and_b32_e32 v53, 0xffff0000, v45
	v_and_b32_e32 v85, 0xffff0000, v77
	v_and_b32_e32 v117, 0xffff0000, v109
	v_and_b32_e32 v149, 0xffff0000, v141
	v_lshlrev_b32_e32 v54, 16, v49
	v_lshlrev_b32_e32 v86, 16, v81
	v_lshlrev_b32_e32 v118, 16, v113
	v_lshlrev_b32_e32 v150, 16, v145
	v_mul_f32_e32 v41, 0xbfb8aa3b, v54
	v_mul_f32_e32 v73, 0xbfb8aa3b, v86
	v_mul_f32_e32 v105, 0xbfb8aa3b, v118
	v_mul_f32_e32 v137, 0xbfb8aa3b, v150
	v_exp_f32_e32 v41, v41
	v_exp_f32_e32 v73, v73
	v_exp_f32_e32 v105, v105
	v_exp_f32_e32 v137, v137
	v_and_b32_e32 v55, 0xffff0000, v49
	v_and_b32_e32 v87, 0xffff0000, v81
	v_and_b32_e32 v119, 0xffff0000, v113
	v_and_b32_e32 v151, 0xffff0000, v145
	v_and_b32_e32 v45, 0xffff0000, v48
	v_and_b32_e32 v77, 0xffff0000, v80
	v_and_b32_e32 v109, 0xffff0000, v112
	v_and_b32_e32 v141, 0xffff0000, v144
	v_lshlrev_b32_e32 v60, 16, v47
	v_lshlrev_b32_e32 v92, 16, v79
	v_lshlrev_b32_e32 v124, 16, v111
	v_lshlrev_b32_e32 v156, 16, v143
	v_add_f32_e32 v41, 1.0, v41
	v_add_f32_e32 v73, 1.0, v73
	v_add_f32_e32 v105, 1.0, v105
	v_add_f32_e32 v137, 1.0, v137
	v_rcp_f32_e32 v58, v41
	v_rcp_f32_e32 v90, v73
	v_rcp_f32_e32 v122, v105
	v_rcp_f32_e32 v154, v137
	v_mul_f32_e32 v41, 0xbfb8aa3b, v55
	v_mul_f32_e32 v73, 0xbfb8aa3b, v87
	v_mul_f32_e32 v105, 0xbfb8aa3b, v119
	v_mul_f32_e32 v137, 0xbfb8aa3b, v151
	v_exp_f32_e32 v41, v41
	v_exp_f32_e32 v73, v73
	v_exp_f32_e32 v105, v105
	v_exp_f32_e32 v137, v137
	v_and_b32_e32 v61, 0xffff0000, v47
	v_and_b32_e32 v93, 0xffff0000, v79
	v_and_b32_e32 v125, 0xffff0000, v111
	v_and_b32_e32 v157, 0xffff0000, v143
	v_add_f32_e32 v41, 1.0, v41
	v_add_f32_e32 v73, 1.0, v73
	v_add_f32_e32 v105, 1.0, v105
	v_add_f32_e32 v137, 1.0, v137
	v_rcp_f32_e32 v59, v41
	v_rcp_f32_e32 v91, v73
	v_rcp_f32_e32 v123, v105
	v_rcp_f32_e32 v155, v137
	s_nop 0
	v_pk_mul_f32 v[54:55], v[58:59], v[54:55]
	v_pk_mul_f32 v[86:87], v[90:91], v[86:87]
	v_pk_mul_f32 v[118:119], v[122:123], v[118:119]
	v_pk_mul_f32 v[150:151], v[154:155], v[150:151]
	v_lshlrev_b32_e32 v58, 16, v44
	v_lshlrev_b32_e32 v90, 16, v76
	v_lshlrev_b32_e32 v122, 16, v108
	v_lshlrev_b32_e32 v154, 16, v140
	v_and_b32_e32 v59, 0xffff0000, v44
	v_and_b32_e32 v91, 0xffff0000, v76
	v_and_b32_e32 v123, 0xffff0000, v108
	v_and_b32_e32 v155, 0xffff0000, v140
	v_lshlrev_b32_e32 v44, 16, v48
	v_lshlrev_b32_e32 v76, 16, v80
	v_lshlrev_b32_e32 v108, 16, v112
	v_lshlrev_b32_e32 v140, 16, v144
	v_mul_f32_e32 v41, 0xbfb8aa3b, v44
	v_mul_f32_e32 v73, 0xbfb8aa3b, v76
	v_mul_f32_e32 v105, 0xbfb8aa3b, v108
	v_mul_f32_e32 v137, 0xbfb8aa3b, v140
	v_exp_f32_e32 v41, v41
	v_exp_f32_e32 v73, v73
	v_exp_f32_e32 v105, v105
	v_exp_f32_e32 v137, v137
	v_pk_mul_f32 v[52:53], v[54:55], v[52:53]
	v_pk_mul_f32 v[84:85], v[86:87], v[84:85]
	v_pk_mul_f32 v[116:117], v[118:119], v[116:117]
	v_pk_mul_f32 v[148:149], v[150:151], v[148:149]
	v_add_f32_e32 v41, 1.0, v41
	v_add_f32_e32 v73, 1.0, v73
	v_add_f32_e32 v105, 1.0, v105
	v_add_f32_e32 v137, 1.0, v137
	v_rcp_f32_e32 v48, v41
	v_rcp_f32_e32 v80, v73
	v_rcp_f32_e32 v112, v105
	v_rcp_f32_e32 v144, v137
	v_mul_f32_e32 v41, 0xbfb8aa3b, v45
	v_mul_f32_e32 v73, 0xbfb8aa3b, v77
	v_mul_f32_e32 v105, 0xbfb8aa3b, v109
	v_mul_f32_e32 v137, 0xbfb8aa3b, v141
	v_exp_f32_e32 v41, v41
	v_exp_f32_e32 v73, v73
	v_exp_f32_e32 v105, v105
	v_exp_f32_e32 v137, v137
	v_pk_mul_f32 v[54:55], v[52:53], v[52:53]
	v_pk_mul_f32 v[86:87], v[84:85], v[84:85]
	v_pk_mul_f32 v[118:119], v[116:117], v[116:117]
	v_pk_mul_f32 v[150:151], v[148:149], v[148:149]
; DI float siluf_(float x) { return x * sigmoidf_(x); }
; DI void unpack8(const u32x4& w, float* f) { f[0] = bflo(w.x); f[1] = bfhi(w.x); f[2] = bflo(w.y); f[3] = bfhi(w.y); f[4] = bflo(w.z); f[5] = bfhi(w.z); f[6] = bflo(w.w); f[7] = bfhi(w.w); }
; DI u32x4 pack8(const float* f) { u32x4 w; w.x = pk2(f[0], f[1]); w.y = pk2(f[2], f[3]); w.z = pk2(f[4], f[5]); w.w = pk2(f[6], f[7]); return w; }
; DI float rs_of(float ss, float inv_n) { return __builtin_amdgcn_rsqf(ss * inv_n + EPS); }
; DI void ssd_norm(const Params& P) {
;     ...
;     for (int item = gw; item < T * 4; item += NW) { const size_t off = (size_t)(item >> 2) * 2048 + (item & 3) * 512 + lane * 8;
;         const u32x4 yw = *(const u32x4*)(YB + off), zw = *(const u32x4*)(Z + off); float f[8], z[8]; unpack8(yw, f); unpack8(zw, z);
;         float sq = 0.f;
; #pragma unroll
;         for (int j = 0; j < 8; ++j) { f[j] *= siluf_(z[j]); sq += f[j] * f[j]; }
; #pragma unroll
;         for (int o = 32; o >= 1; o >>= 1) sq += __shfl_xor(sq, o);
;         const float rs = rs_of(sq, 1.f / 512.f);
; #pragma unroll
;         for (int j = 0; j < 8; ++j) f[j] *= rs;
;         *(u32x4*)(YB + off) = pack8(f); }
	v_add_f32_e32 v41, 1.0, v41
	v_add_f32_e32 v73, 1.0, v73
	v_add_f32_e32 v105, 1.0, v105
	v_add_f32_e32 v137, 1.0, v137
	v_rcp_f32_e32 v49, v41
	v_rcp_f32_e32 v81, v73
	v_rcp_f32_e32 v113, v105
	v_rcp_f32_e32 v145, v137
	v_mul_f32_e32 v41, 0xbfb8aa3b, v60
	v_mul_f32_e32 v73, 0xbfb8aa3b, v92
	v_mul_f32_e32 v105, 0xbfb8aa3b, v124
	v_mul_f32_e32 v137, 0xbfb8aa3b, v156
	v_exp_f32_e32 v41, v41
	v_exp_f32_e32 v73, v73
	v_exp_f32_e32 v105, v105
	v_exp_f32_e32 v137, v137
	v_pk_mul_f32 v[44:45], v[48:49], v[44:45]
	v_pk_mul_f32 v[76:77], v[80:81], v[76:77]
	v_pk_mul_f32 v[108:109], v[112:113], v[108:109]
	v_pk_mul_f32 v[140:141], v[144:145], v[140:141]
	s_nop 0
	v_pk_mul_f32 v[44:45], v[44:45], v[58:59]
	v_pk_mul_f32 v[76:77], v[76:77], v[90:91]
	v_pk_mul_f32 v[108:109], v[108:109], v[122:123]
	v_pk_mul_f32 v[140:141], v[140:141], v[154:155]
	v_add_f32_e32 v41, 1.0, v41
	v_add_f32_e32 v73, 1.0, v73
	v_add_f32_e32 v105, 1.0, v105
	v_add_f32_e32 v137, 1.0, v137
	v_rcp_f32_e32 v62, v41
	v_rcp_f32_e32 v94, v73
	v_rcp_f32_e32 v126, v105
	v_rcp_f32_e32 v158, v137
	v_mul_f32_e32 v41, 0xbfb8aa3b, v61
	v_mul_f32_e32 v73, 0xbfb8aa3b, v93
	v_mul_f32_e32 v105, 0xbfb8aa3b, v125
	v_mul_f32_e32 v137, 0xbfb8aa3b, v157
	v_exp_f32_e32 v41, v41
	v_exp_f32_e32 v73, v73
	v_exp_f32_e32 v105, v105
	v_exp_f32_e32 v137, v137
	v_lshlrev_b32_e32 v58, 16, v43
	v_lshlrev_b32_e32 v90, 16, v75
	v_lshlrev_b32_e32 v122, 16, v107
	v_lshlrev_b32_e32 v154, 16, v139
	v_and_b32_e32 v59, 0xffff0000, v43
	v_and_b32_e32 v91, 0xffff0000, v75
	v_and_b32_e32 v123, 0xffff0000, v107
	v_and_b32_e32 v155, 0xffff0000, v139
	v_and_b32_e32 v43, 0xffff0000, v46
	v_and_b32_e32 v75, 0xffff0000, v78
	v_and_b32_e32 v107, 0xffff0000, v110
	v_and_b32_e32 v139, 0xffff0000, v142
	v_add_f32_e32 v41, 1.0, v41
	v_add_f32_e32 v73, 1.0, v73
	v_add_f32_e32 v105, 1.0, v105
	v_add_f32_e32 v137, 1.0, v137
	v_rcp_f32_e32 v63, v41
	v_rcp_f32_e32 v95, v73
	v_rcp_f32_e32 v127, v105
	v_rcp_f32_e32 v159, v137
	v_pk_mul_f32 v[48:49], v[44:45], v[44:45]
	v_pk_mul_f32 v[80:81], v[76:77], v[76:77]
	v_pk_mul_f32 v[112:113], v[108:109], v[108:109]
	v_pk_mul_f32 v[144:145], v[140:141], v[140:141]
	v_pk_mul_f32 v[60:61], v[62:63], v[60:61]
	v_pk_mul_f32 v[92:93], v[94:95], v[92:93]
	v_pk_mul_f32 v[124:125], v[126:127], v[124:125]
	v_pk_mul_f32 v[156:157], v[158:159], v[156:157]
	v_lshlrev_b32_e32 v62, 16, v42
	v_lshlrev_b32_e32 v94, 16, v74
	v_lshlrev_b32_e32 v126, 16, v106
	v_lshlrev_b32_e32 v158, 16, v138
	v_and_b32_e32 v63, 0xffff0000, v42
	v_and_b32_e32 v95, 0xffff0000, v74
	v_and_b32_e32 v127, 0xffff0000, v106
	v_and_b32_e32 v159, 0xffff0000, v138
	v_lshlrev_b32_e32 v42, 16, v46
	v_lshlrev_b32_e32 v74, 16, v78
	v_lshlrev_b32_e32 v106, 16, v110
	v_lshlrev_b32_e32 v138, 16, v142
	v_mul_f32_e32 v41, 0xbfb8aa3b, v42
	v_mul_f32_e32 v73, 0xbfb8aa3b, v74
	v_mul_f32_e32 v105, 0xbfb8aa3b, v106
	v_mul_f32_e32 v137, 0xbfb8aa3b, v138
	v_exp_f32_e32 v41, v41
	v_exp_f32_e32 v73, v73
	v_exp_f32_e32 v105, v105
	v_exp_f32_e32 v137, v137
	v_pk_mul_f32 v[58:59], v[60:61], v[58:59]
	v_pk_mul_f32 v[90:91], v[92:93], v[90:91]
	v_pk_mul_f32 v[122:123], v[124:125], v[122:123]
	v_pk_mul_f32 v[154:155], v[156:157], v[154:155]
	v_add_f32_e32 v41, 1.0, v41
	v_add_f32_e32 v73, 1.0, v73
	v_add_f32_e32 v105, 1.0, v105
	v_add_f32_e32 v137, 1.0, v137
	v_rcp_f32_e32 v46, v41
	v_rcp_f32_e32 v78, v73
	v_rcp_f32_e32 v110, v105
	v_rcp_f32_e32 v142, v137
	v_mul_f32_e32 v41, 0xbfb8aa3b, v43
	v_mul_f32_e32 v73, 0xbfb8aa3b, v75
	v_mul_f32_e32 v105, 0xbfb8aa3b, v107
	v_mul_f32_e32 v137, 0xbfb8aa3b, v139
	v_exp_f32_e32 v41, v41
	v_exp_f32_e32 v73, v73
	v_exp_f32_e32 v105, v105
	v_exp_f32_e32 v137, v137
	v_pk_mul_f32 v[60:61], v[58:59], v[58:59]
	v_pk_mul_f32 v[92:93], v[90:91], v[90:91]
	v_pk_mul_f32 v[124:125], v[122:123], v[122:123]
	v_pk_mul_f32 v[156:157], v[154:155], v[154:155]
	v_add_f32_e32 v41, 1.0, v41
	v_add_f32_e32 v73, 1.0, v73
	v_add_f32_e32 v105, 1.0, v105
	v_add_f32_e32 v137, 1.0, v137
	v_rcp_f32_e32 v47, v41
	v_rcp_f32_e32 v79, v73
	v_rcp_f32_e32 v111, v105
	v_rcp_f32_e32 v143, v137
	s_nop 0
	v_pk_mul_f32 v[42:43], v[46:47], v[42:43]
	v_pk_mul_f32 v[74:75], v[78:79], v[74:75]
	v_pk_mul_f32 v[106:107], v[110:111], v[106:107]
	v_pk_mul_f32 v[138:139], v[142:143], v[138:139]
	s_nop 0
	v_pk_mul_f32 v[42:43], v[42:43], v[62:63]
	v_pk_mul_f32 v[74:75], v[74:75], v[94:95]
	v_pk_mul_f32 v[106:107], v[106:107], v[126:127]
	v_pk_mul_f32 v[138:139], v[138:139], v[158:159]
	s_nop 0
	v_pk_mul_f32 v[46:47], v[42:43], v[42:43]
	v_pk_mul_f32 v[78:79], v[74:75], v[74:75]
	v_pk_mul_f32 v[110:111], v[106:107], v[106:107]
	v_pk_mul_f32 v[142:143], v[138:139], v[138:139]
	s_nop 0
	v_add_f32_e32 v41, v46, v47
	v_add_f32_e32 v73, v78, v79
	v_add_f32_e32 v105, v110, v111
	v_add_f32_e32 v137, v142, v143
	v_add_f32_e32 v41, v60, v41
	v_add_f32_e32 v73, v92, v73
	v_add_f32_e32 v105, v124, v105
	v_add_f32_e32 v137, v156, v137
	v_add_f32_e32 v41, v61, v41
	v_add_f32_e32 v73, v93, v73
	v_add_f32_e32 v105, v125, v105
	v_add_f32_e32 v137, v157, v137
	v_add_f32_e32 v41, v48, v41
	v_add_f32_e32 v73, v80, v73
	v_add_f32_e32 v105, v112, v105
	v_add_f32_e32 v137, v144, v137
	v_add_f32_e32 v41, v49, v41
	v_add_f32_e32 v73, v81, v73
	v_add_f32_e32 v105, v113, v105
	v_add_f32_e32 v137, v145, v137
	v_add_f32_e32 v41, v54, v41
	v_add_f32_e32 v73, v86, v73
	v_add_f32_e32 v105, v118, v105
	v_add_f32_e32 v137, v150, v137
	v_add_f32_e32 v41, v55, v41
	v_add_f32_e32 v73, v87, v73
	v_add_f32_e32 v105, v119, v105
	v_add_f32_e32 v137, v151, v137
	ds_bpermute_b32 v46, v2, v41
	ds_bpermute_b32 v78, v2, v73
	ds_bpermute_b32 v110, v2, v105
	ds_bpermute_b32 v142, v2, v137
	s_waitcnt lgkmcnt(0)
; DI float siluf_(float x) { return x * sigmoidf_(x); }
; DI void unpack8(const u32x4& w, float* f) { f[0] = bflo(w.x); f[1] = bfhi(w.x); f[2] = bflo(w.y); f[3] = bfhi(w.y); f[4] = bflo(w.z); f[5] = bfhi(w.z); f[6] = bflo(w.w); f[7] = bfhi(w.w); }
; DI u32x4 pack8(const float* f) { u32x4 w; w.x = pk2(f[0], f[1]); w.y = pk2(f[2], f[3]); w.z = pk2(f[4], f[5]); w.w = pk2(f[6], f[7]); return w; }
; DI float rs_of(float ss, float inv_n) { return __builtin_amdgcn_rsqf(ss * inv_n + EPS); }
; DI void ssd_norm(const Params& P) {
;     ...
;     for (int item = gw; item < T * 4; item += NW) { const size_t off = (size_t)(item >> 2) * 2048 + (item & 3) * 512 + lane * 8;
;         const u32x4 yw = *(const u32x4*)(YB + off), zw = *(const u32x4*)(Z + off); float f[8], z[8]; unpack8(yw, f); unpack8(zw, z);
;         float sq = 0.f;
; #pragma unroll
;         for (int j = 0; j < 8; ++j) { f[j] *= siluf_(z[j]); sq += f[j] * f[j]; }
; #pragma unroll
;         for (int o = 32; o >= 1; o >>= 1) sq += __shfl_xor(sq, o);
;         const float rs = rs_of(sq, 1.f / 512.f);
; #pragma unroll
;         for (int j = 0; j < 8; ++j) f[j] *= rs;
;         *(u32x4*)(YB + off) = pack8(f); }
	v_add_f32_e32 v41, v41, v46
	v_add_f32_e32 v73, v73, v78
	v_add_f32_e32 v105, v105, v110
	v_add_f32_e32 v137, v137, v142
	ds_bpermute_b32 v46, v3, v41
	ds_bpermute_b32 v78, v3, v73
	ds_bpermute_b32 v110, v3, v105
	ds_bpermute_b32 v142, v3, v137
	s_waitcnt lgkmcnt(0)
	v_add_f32_e32 v41, v41, v46
	v_add_f32_e32 v73, v73, v78
	v_add_f32_e32 v105, v105, v110
	v_add_f32_e32 v137, v137, v142
	ds_bpermute_b32 v46, v4, v41
	ds_bpermute_b32 v78, v4, v73
	ds_bpermute_b32 v110, v4, v105
	ds_bpermute_b32 v142, v4, v137
	s_waitcnt lgkmcnt(0)
	v_add_f32_e32 v41, v41, v46
	v_add_f32_e32 v73, v73, v78
	v_add_f32_e32 v105, v105, v110
	v_add_f32_e32 v137, v137, v142
	ds_bpermute_b32 v46, v5, v41
	ds_bpermute_b32 v78, v5, v73
	ds_bpermute_b32 v110, v5, v105
	ds_bpermute_b32 v142, v5, v137
	s_waitcnt lgkmcnt(0)
	v_add_f32_e32 v41, v41, v46
	v_add_f32_e32 v73, v73, v78
	v_add_f32_e32 v105, v105, v110
	v_add_f32_e32 v137, v137, v142
	ds_bpermute_b32 v46, v6, v41
	ds_bpermute_b32 v78, v6, v73
	ds_bpermute_b32 v110, v6, v105
	ds_bpermute_b32 v142, v6, v137
	s_waitcnt lgkmcnt(0)
	v_add_f32_e32 v41, v41, v46
	v_add_f32_e32 v73, v73, v78
	v_add_f32_e32 v105, v105, v110
	v_add_f32_e32 v137, v137, v142
	ds_bpermute_b32 v46, v7, v41
	ds_bpermute_b32 v78, v7, v73
	ds_bpermute_b32 v110, v7, v105
	ds_bpermute_b32 v142, v7, v137
	s_waitcnt lgkmcnt(0)
	v_add_f32_e32 v41, v41, v46
	v_add_f32_e32 v73, v73, v78
	v_add_f32_e32 v105, v105, v110
	v_add_f32_e32 v137, v137, v142
	v_fmamk_f32 v41, v41, 0x3b000000, v185
	v_fmamk_f32 v73, v73, 0x3b000000, v185
	v_fmamk_f32 v105, v105, 0x3b000000, v185
	v_fmamk_f32 v137, v137, 0x3b000000, v185
	v_rsq_f32_e32 v46, v41
	v_rsq_f32_e32 v78, v73
	v_rsq_f32_e32 v110, v105
	v_rsq_f32_e32 v142, v137
	s_nop 0
	v_pk_mul_f32 v[42:43], v[42:43], v[46:47] op_sel_hi:[1,0]
	v_pk_mul_f32 v[74:75], v[74:75], v[78:79] op_sel_hi:[1,0]
	v_pk_mul_f32 v[106:107], v[106:107], v[110:111] op_sel_hi:[1,0]
	v_pk_mul_f32 v[138:139], v[138:139], v[142:143] op_sel_hi:[1,0]
	v_pk_mul_f32 v[48:49], v[58:59], v[46:47] op_sel_hi:[1,0]
	v_pk_mul_f32 v[80:81], v[90:91], v[78:79] op_sel_hi:[1,0]
	v_pk_mul_f32 v[112:113], v[122:123], v[110:111] op_sel_hi:[1,0]
	v_pk_mul_f32 v[144:145], v[154:155], v[142:143] op_sel_hi:[1,0]
	v_pk_mul_f32 v[44:45], v[44:45], v[46:47] op_sel_hi:[1,0]
	v_pk_mul_f32 v[76:77], v[76:77], v[78:79] op_sel_hi:[1,0]
	v_pk_mul_f32 v[108:109], v[108:109], v[110:111] op_sel_hi:[1,0]
	v_pk_mul_f32 v[140:141], v[140:141], v[142:143] op_sel_hi:[1,0]
	v_pk_mul_f32 v[46:47], v[52:53], v[46:47] op_sel_hi:[1,0]
	v_pk_mul_f32 v[78:79], v[84:85], v[78:79] op_sel_hi:[1,0]
	v_pk_mul_f32 v[110:111], v[116:117], v[110:111] op_sel_hi:[1,0]
	v_pk_mul_f32 v[142:143], v[148:149], v[142:143] op_sel_hi:[1,0]
	v_cvt_pk_bf16_f32 v42, v42, v43
	v_cvt_pk_bf16_f32 v74, v74, v75
	v_cvt_pk_bf16_f32 v106, v106, v107
	v_cvt_pk_bf16_f32 v138, v138, v139
	v_cvt_pk_bf16_f32 v43, v48, v49
	v_cvt_pk_bf16_f32 v75, v80, v81
	v_cvt_pk_bf16_f32 v107, v112, v113
	v_cvt_pk_bf16_f32 v139, v144, v145
	v_cvt_pk_bf16_f32 v44, v44, v45
	v_cvt_pk_bf16_f32 v76, v76, v77
	v_cvt_pk_bf16_f32 v108, v108, v109
	v_cvt_pk_bf16_f32 v140, v140, v141
	v_cvt_pk_bf16_f32 v45, v46, v47
	v_cvt_pk_bf16_f32 v77, v78, v79
	v_cvt_pk_bf16_f32 v109, v110, v111
	v_cvt_pk_bf16_f32 v141, v142, v143
	global_store_dwordx4 v[50:51], v[42:45], off
	global_store_dwordx4 v[82:83], v[74:77], off
	global_store_dwordx4 v[114:115], v[106:109], off
	global_store_dwordx4 v[146:147], v[138:141], off
	v_readfirstlane_b32 s14, v1
	s_nop 3
	s_cmp_gt_i32 s14, 0x107ff
	s_cbranch_scc0 .Lnorm4
	s_branch .LBB0_167
